# P1 de-phasing in three groups ((block>>3) mod 3): start delays 0 / 5 / 10 us instead of two groups 0 / 10 us
# baseline (speedup 1.0000x reference)
.LBB0_107:
	v_writelane_b32 v254, s59, 20
	v_writelane_b32 v254, s60, 21
	s_nop 1
	v_writelane_b32 v254, s61, 22
	s_or_b64 exec, exec, s[0:1]
	s_add_u32 s56, s90, 0x5f6ea00
	s_addc_u32 s57, s91, 0
	s_add_u32 s40, s90, 0x3eeea00
	s_addc_u32 s41, s91, 0
	s_add_u32 s96, s90, 0x6faea00
	s_addc_u32 s97, s91, 0
	s_add_u32 s0, s90, 0x7feea00
	s_addc_u32 s1, s91, 0
	v_writelane_b32 v254, s0, 23
	v_mov_b32_e32 v12, v0
	s_waitcnt lgkmcnt(0)
	v_writelane_b32 v254, s1, 24
	s_add_u32 s0, s90, 0x902ea00
	s_addc_u32 s1, s91, 0
	v_writelane_b32 v254, s0, 25
	s_add_u32 s94, s90, 0x1e6ea00
	s_addc_u32 s95, s91, 0
	v_writelane_b32 v254, s1, 26
	s_barrier
	v_readlane_b32 s27, v254, 20
	s_lshr_b32 s0, s27, 3
	s_mul_i32 s1, s0, 11
	s_lshr_b32 s1, s1, 5
	s_mul_i32 s1, s1, 3
	s_sub_i32 s0, s0, s1
	s_cmp_eq_u32 s0, 0
	s_cbranch_scc1 .Lstg1_done
	s_sleep 127
	s_sleep 60
	s_cmp_eq_u32 s0, 1
	s_cbranch_scc1 .Lstg1_done
	s_sleep 127
	s_sleep 60
